# prologue int8 copy loop: row-gain loads batched with data loads, column-max loads hoisted
# speedup vs baseline: 1.0104x; 1.0021x over previous
; #define GAS __attribute__((address_space(1)))
; #define LAS __attribute__((address_space(3)))
; #define LDS_WAIT() asm volatile("s_waitcnt lgkmcnt(0)" ::: "memory")
; __device__ __forceinline__ void transpose_item_q(const float* __restrict__ W, int K, int N, signed char* __restrict__ WQ, const float* __restrict__ gk, const unsigned* __restrict__ cmax, LAS float* scr, int item, int lane, int* csum = nullptr) {
;     const int nblk = N / 32, kb = item / nblk, nb = item - kb * nblk, k0 = 64 * kb, n0 = 32 * nb;
;     const int rr = lane >> 3, c4 = (lane & 7) * 4;
; #pragma unroll
;     for (int hb = 0; hb < 2; ++hb) {
;         f32x4 v[4];
; #pragma unroll
;         for (int i = 0; i < 4; ++i) v[i] = *(const GAS f32x4*)(W + (size_t)(k0 + 8 * (4 * hb + i) + rr) * N + n0 + c4);
; #pragma unroll
;         for (int i = 0; i < 4; ++i) { if (gk) v[i] = v[i] * gk[k0 + 8 * (4 * hb + i) + rr]; }
; #pragma unroll
;         for (int i = 0; i < 4; ++i) { LAS float* d = scr + (8 * (4 * hb + i) + rr) * 33 + c4; d[0] = v[i].x; d[1] = v[i].y; d[2] = v[i].z; d[3] = v[i].w; }
;         asm volatile("" ::: "memory");
;     }
;     LDS_WAIT(); asm volatile("" ::: "memory");
;     const int c = lane & 3;
; #pragma unroll
;     for (int j = 0; j < 2; ++j) { const int n = (lane >> 2) + 16 * j; const LAS float* s = scr + (16 * c) * 33 + n;
;         const float inv = 127.0f / fmaxf(__uint_as_float(cmax[n0 + n]), 1e-30f);
.LBB0_31:
	s_abs_i32 s15, s86
	s_mul_hi_u32 s18, s15, s85
	s_mul_i32 s19, s18, s68
	s_sub_i32 s15, s15, s19
	s_ashr_i32 s14, s86, 31
	s_add_i32 s19, s18, 1
	s_sub_i32 s31, s15, s68
	s_cmp_ge_u32 s15, s68
	s_cselect_b32 s18, s19, s18
	s_cselect_b32 s15, s31, s15
	s_add_i32 s19, s18, 1
	s_cmp_ge_u32 s15, s68
	s_cselect_b32 s15, s19, s18
	s_xor_b32 s15, s15, s14
	s_sub_i32 s34, s15, s14
	s_lshl_b32 s31, s34, 6
	v_add_u32_e32 v30, s31, v32
	v_add_u32_e32 v10, 16, v30
	v_mad_u64_u32 v[2:3], s[48:49], v30, s2, 0
	v_ashrrev_i32_e32 v13, 31, v10
	v_mad_u64_u32 v[10:11], s[48:49], v10, s2, 0
	v_ashrrev_i32_e32 v31, 31, v30
	v_mov_b32_e32 v4, v3
	v_mov_b32_e32 v12, v11
	v_mad_u64_u32 v[4:5], s[48:49], v31, s2, v[4:5]
	v_mad_u64_u32 v[12:13], s[48:49], v13, s2, v[12:13]
	s_mul_i32 s14, s87, s34
	v_mov_b32_e32 v3, v4
	v_add_u32_e32 v4, 8, v30
	v_mov_b32_e32 v11, v12
	v_add_u32_e32 v12, 24, v30
	s_add_i32 s44, s25, s14
	v_add_u32_e32 v58, s44, v36
	v_ashrrev_i32_e32 v59, 31, v58
	v_lshl_add_u64 v[58:59], v[58:59], 2, s[64:65]
	global_load_dword v60, v[58:59], off
	global_load_dword v61, v[58:59], off offset:64
	v_ashrrev_i32_e32 v7, 31, v4
	v_mad_u64_u32 v[4:5], s[48:49], v4, s2, 0
	v_ashrrev_i32_e32 v15, 31, v12
	v_mad_u64_u32 v[12:13], s[48:49], v12, s2, 0
	s_sub_i32 s18, s44, 32
	v_mov_b32_e32 v6, v5
	v_mov_b32_e32 v14, v13
	s_ashr_i32 s19, s18, 31
	v_mad_u64_u32 v[6:7], s[48:49], v7, s2, v[6:7]
	v_mad_u64_u32 v[14:15], s[48:49], v15, s2, v[14:15]
	s_waitcnt lgkmcnt(0)
	v_lshl_add_u64 v[28:29], s[18:19], 2, v[18:19]
	v_mov_b32_e32 v5, v6
	v_mov_b32_e32 v13, v14
	v_lshl_add_u64 v[2:3], v[2:3], 2, v[28:29]
	v_lshl_add_u64 v[4:5], v[4:5], 2, v[28:29]
	v_lshl_add_u64 v[10:11], v[10:11], 2, v[28:29]
	v_lshl_add_u64 v[12:13], v[12:13], 2, v[28:29]
	global_load_dwordx4 v[6:9], v[2:3], off
	s_nop 0
	global_load_dwordx4 v[2:5], v[4:5], off
	s_nop 0
	global_load_dwordx4 v[14:17], v[10:11], off
	s_nop 0
	global_load_dwordx4 v[10:13], v[12:13], off
	v_cndmask_b32_e64 v26, 0, 1, s[36:37]
	v_cmp_ne_u32_e64 s[48:49], 1, v26
	s_andn2_b64 vcc, exec, s[36:37]
	v_lshl_add_u64 v[26:27], v[30:31], 2, s[88:89]
	s_cbranch_vccnz .LBB0_39
	global_load_dword v38, v[26:27], off
	global_load_dword v52, v[26:27], off offset:32
	global_load_dword v54, v[26:27], off offset:64
	global_load_dword v56, v[26:27], off offset:96
	s_waitcnt vmcnt(0)
	v_pk_mul_f32 v[8:9], v[8:9], v[38:39] op_sel_hi:[1,0]
	v_pk_mul_f32 v[6:7], v[6:7], v[38:39] op_sel_hi:[1,0]
	v_pk_mul_f32 v[4:5], v[4:5], v[52:53] op_sel_hi:[1,0]
	v_pk_mul_f32 v[2:3], v[2:3], v[52:53] op_sel_hi:[1,0]
	v_pk_mul_f32 v[16:17], v[16:17], v[54:55] op_sel_hi:[1,0]
	v_pk_mul_f32 v[14:15], v[14:15], v[54:55] op_sel_hi:[1,0]
	v_pk_mul_f32 v[12:13], v[12:13], v[56:57] op_sel_hi:[1,0]
	v_pk_mul_f32 v[10:11], v[10:11], v[56:57] op_sel_hi:[1,0]
.LBB0_39:
	s_waitcnt vmcnt(3)
	ds_write2_b32 v37, v6, v7 offset1:1
	ds_write2_b32 v37, v8, v9 offset0:2 offset1:3
	v_add_u32_e32 v6, 0x420, v37
	s_waitcnt vmcnt(2)
	ds_write2_b32 v6, v2, v3 offset1:1
	v_add_u32_e32 v2, 0x428, v37
	ds_write2_b32 v2, v4, v5 offset1:1
	v_add_u32_e32 v2, 0x840, v37
	s_waitcnt vmcnt(1)
	ds_write2_b32 v2, v14, v15 offset1:1
	v_add_u32_e32 v2, 0x848, v37
	ds_write2_b32 v2, v16, v17 offset1:1
	v_add_u32_e32 v2, 0xc60, v37
	s_waitcnt vmcnt(0)
	ds_write2_b32 v2, v10, v11 offset1:1
	v_add_u32_e32 v2, 0xc68, v37
	ds_write2_b32 v2, v12, v13 offset1:1
	v_add_u32_e32 v2, 32, v30
	v_add_u32_e32 v10, 48, v30
	v_ashrrev_i32_e32 v5, 31, v2
	v_mad_u64_u32 v[2:3], vcc, v2, s2, 0
	v_ashrrev_i32_e32 v13, 31, v10
	v_mad_u64_u32 v[10:11], vcc, v10, s2, 0
	v_mov_b32_e32 v4, v3
	v_mov_b32_e32 v12, v11
	v_mad_u64_u32 v[4:5], vcc, v5, s2, v[4:5]
	v_mad_u64_u32 v[12:13], vcc, v13, s2, v[12:13]
	v_mov_b32_e32 v3, v4
	v_add_u32_e32 v4, 40, v30
	v_mov_b32_e32 v11, v12
	v_add_u32_e32 v12, 56, v30
	v_ashrrev_i32_e32 v7, 31, v4
	v_mad_u64_u32 v[4:5], vcc, v4, s2, 0
	v_ashrrev_i32_e32 v15, 31, v12
	v_mad_u64_u32 v[12:13], vcc, v12, s2, 0
	v_mov_b32_e32 v6, v5
	v_mov_b32_e32 v14, v13
	v_mad_u64_u32 v[6:7], vcc, v7, s2, v[6:7]
	v_mad_u64_u32 v[14:15], vcc, v15, s2, v[14:15]
	v_mov_b32_e32 v5, v6
	v_mov_b32_e32 v13, v14
	v_lshl_add_u64 v[2:3], v[2:3], 2, v[28:29]
	v_lshl_add_u64 v[4:5], v[4:5], 2, v[28:29]
	v_lshl_add_u64 v[10:11], v[10:11], 2, v[28:29]
	v_lshl_add_u64 v[12:13], v[12:13], 2, v[28:29]
	global_load_dwordx4 v[6:9], v[2:3], off
	s_nop 0
	global_load_dwordx4 v[2:5], v[4:5], off
	s_nop 0
	global_load_dwordx4 v[14:17], v[10:11], off
	s_nop 0
	global_load_dwordx4 v[10:13], v[12:13], off
	s_and_b64 vcc, exec, s[48:49]
	s_cbranch_vccnz .LBB0_47
	global_load_dword v28, v[26:27], off offset:128
	global_load_dword v52, v[26:27], off offset:160
	global_load_dword v54, v[26:27], off offset:192
	global_load_dword v56, v[26:27], off offset:224
	s_waitcnt vmcnt(0)
	v_pk_mul_f32 v[8:9], v[8:9], v[28:29] op_sel_hi:[1,0]
	v_pk_mul_f32 v[6:7], v[6:7], v[28:29] op_sel_hi:[1,0]
	v_pk_mul_f32 v[4:5], v[4:5], v[52:53] op_sel_hi:[1,0]
	v_pk_mul_f32 v[2:3], v[2:3], v[52:53] op_sel_hi:[1,0]
	v_pk_mul_f32 v[16:17], v[16:17], v[54:55] op_sel_hi:[1,0]
	v_pk_mul_f32 v[14:15], v[14:15], v[54:55] op_sel_hi:[1,0]
	v_pk_mul_f32 v[12:13], v[12:13], v[56:57] op_sel_hi:[1,0]
	v_pk_mul_f32 v[10:11], v[10:11], v[56:57] op_sel_hi:[1,0]
; #define LAS __attribute__((address_space(3)))
; #define LDS_WAIT() asm volatile("s_waitcnt lgkmcnt(0)" ::: "memory")
; __device__ __forceinline__ int q8(float v) { int q = (int)rintf(v); q = q < -127 ? -127 : q; return q > 127 ? 127 : q; }
; __device__ __forceinline__ unsigned pkq4(int a, int b, int c, int d) { return (unsigned)(a & 255) | ((unsigned)(b & 255) << 8) | ((unsigned)(c & 255) << 16) | ((unsigned)d << 24); }
; __device__ __forceinline__ void transpose_item_q(const float* __restrict__ W, int K, int N, signed char* __restrict__ WQ, const float* __restrict__ gk, const unsigned* __restrict__ cmax, LAS float* scr, int item, int lane, int* csum = nullptr) {
;     ...
;     LDS_WAIT(); asm volatile("" ::: "memory");
;     const int c = lane & 3;
; #pragma unroll
;     for (int j = 0; j < 2; ++j) { const int n = (lane >> 2) + 16 * j; const LAS float* s = scr + (16 * c) * 33 + n;
;         const float inv = 127.0f / fmaxf(__uint_as_float(cmax[n0 + n]), 1e-30f);
;         int q[16];
; #pragma unroll
;         for (int e = 0; e < 16; ++e) q[e] = q8(s[e * 33] * inv);
;         v4u o; o.x = pkq4(q[0], q[1], q[2], q[3]); o.y = pkq4(q[4], q[5], q[6], q[7]); o.z = pkq4(q[8], q[9], q[10], q[11]); o.w = pkq4(q[12], q[13], q[14], q[15]);
;         if (csum) { int t = 0;
; #pragma unroll
;             for (int e = 0; e < 16; ++e) t += q[e];
;             t += __builtin_amdgcn_ds_bpermute((lane ^ 1) << 2, t); t += __builtin_amdgcn_ds_bpermute((lane ^ 2) << 2, t);
;             if (c == 0) (void)__hip_atomic_fetch_add(csum + n0 + n, t, __ATOMIC_RELAXED, __HIP_MEMORY_SCOPE_AGENT); }
.LBB0_47:
	v_add_u32_e32 v26, 0x1080, v37
	s_waitcnt vmcnt(3)
	ds_write2_b32 v26, v6, v7 offset1:1
	v_add_u32_e32 v6, 0x1088, v37
	ds_write2_b32 v6, v8, v9 offset1:1
	v_add_u32_e32 v6, 0x14a0, v37
	s_waitcnt vmcnt(2)
	ds_write2_b32 v6, v2, v3 offset1:1
	v_add_u32_e32 v2, 0x14a8, v37
	ds_write2_b32 v2, v4, v5 offset1:1
	v_add_u32_e32 v2, 0x18c0, v37
	s_waitcnt vmcnt(1)
	ds_write2_b32 v2, v14, v15 offset1:1
	v_add_u32_e32 v2, 0x18c8, v37
	ds_write2_b32 v2, v16, v17 offset1:1
	v_add_u32_e32 v2, 0x1ce0, v37
	s_waitcnt vmcnt(0)
	ds_write2_b32 v2, v10, v11 offset1:1
	v_add_u32_e32 v2, 0x1ce8, v37
	ds_write2_b32 v2, v12, v13 offset1:1
	v_add_u32_e32 v2, s44, v36
	s_waitcnt lgkmcnt(0)
	v_ashrrev_i32_e32 v3, 31, v2
	v_lshl_add_u64 v[2:3], v[2:3], 2, s[64:65]
	v_mov_b32_e32 v5, v60
	v_add_u32_e32 v4, 0x400, v35
	ds_read2_b32 v[6:7], v35 offset1:33
	ds_read2_b32 v[8:9], v35 offset0:66 offset1:99
	ds_read2_b32 v[10:11], v35 offset0:132 offset1:165
	ds_read2_b32 v[12:13], v35 offset0:198 offset1:231
	ds_read2_b32 v[14:15], v4 offset0:8 offset1:41
	ds_read2_b32 v[16:17], v4 offset0:74 offset1:107
	ds_read2_b32 v[26:27], v4 offset0:140 offset1:173
	ds_read2_b32 v[28:29], v4 offset0:206 offset1:239
	s_lshl_b64 s[44:45], s[18:19], 2
	s_add_u32 s44, s66, s44
	s_addc_u32 s45, s67, s45
	s_waitcnt vmcnt(0)
	v_max_f32_e32 v5, v5, v5
	v_max_f32_e32 v5, 0xda24260, v5
	v_div_scale_f32 v30, s[48:49], v5, v5, s0
	v_rcp_f32_e32 v31, v30
	v_div_scale_f32 v38, vcc, s0, v5, s0
	v_fma_f32 v39, -v30, v31, 1.0
	v_fmac_f32_e32 v31, v39, v31
	v_mul_f32_e32 v39, v38, v31
	v_fma_f32 v40, -v30, v39, v38
	v_fmac_f32_e32 v39, v40, v31
	v_fma_f32 v30, -v30, v39, v38
	v_div_fmas_f32 v30, v30, v31, v39
	v_div_fixup_f32 v30, v30, v5, s0
	s_waitcnt lgkmcnt(7)
	v_mul_f32_e32 v5, v6, v30
	v_mul_f32_e32 v6, v30, v7
	s_waitcnt lgkmcnt(6)
	v_mul_f32_e32 v7, v30, v8
	v_mul_f32_e32 v8, v30, v9
	v_rndne_f32_e32 v8, v8
	s_waitcnt lgkmcnt(5)
	v_mul_f32_e32 v9, v30, v10
	v_mul_f32_e32 v10, v30, v11
	s_waitcnt lgkmcnt(4)
	v_mul_f32_e32 v11, v30, v12
	v_mul_f32_e32 v12, v30, v13
	s_waitcnt lgkmcnt(3)
	v_mul_f32_e32 v13, v30, v14
	v_mul_f32_e32 v14, v30, v15
	s_waitcnt lgkmcnt(2)
	v_mul_f32_e32 v15, v30, v16
	v_mul_f32_e32 v16, v30, v17
	s_waitcnt lgkmcnt(1)
	v_mul_f32_e32 v17, v30, v26
	v_mul_f32_e32 v26, v30, v27
	s_waitcnt lgkmcnt(0)
	v_mul_f32_e32 v27, v30, v28
	v_cvt_i32_f32_e32 v28, v8
	v_rndne_f32_e32 v10, v10
	v_cvt_i32_f32_e32 v38, v10
	v_rndne_f32_e32 v5, v5
	v_med3_i32 v10, v28, s1, v118
	v_mul_f32_e32 v28, v30, v29
	v_rndne_f32_e32 v6, v6
	v_rndne_f32_e32 v7, v7
	v_rndne_f32_e32 v9, v9
	v_rndne_f32_e32 v11, v11
	v_rndne_f32_e32 v12, v12
	v_rndne_f32_e32 v13, v13
	v_rndne_f32_e32 v14, v14
	v_rndne_f32_e32 v15, v15
	v_rndne_f32_e32 v16, v16
	v_rndne_f32_e32 v17, v17
	v_rndne_f32_e32 v26, v26
	v_rndne_f32_e32 v27, v27
	v_rndne_f32_e32 v28, v28
	v_cvt_i32_f32_e32 v5, v5
	v_cvt_i32_f32_e32 v6, v6
	v_cvt_i32_f32_e32 v7, v7
	v_cvt_i32_f32_e32 v31, v9
	v_cvt_i32_f32_e32 v11, v11
	v_cvt_i32_f32_e32 v39, v12
	v_cvt_i32_f32_e32 v40, v13
	v_cvt_i32_f32_e32 v41, v14
	v_cvt_i32_f32_e32 v42, v15
	v_cvt_i32_f32_e32 v43, v16
	v_cvt_i32_f32_e32 v44, v17
	v_cvt_i32_f32_e32 v26, v26
	v_cvt_i32_f32_e32 v27, v27
	v_cvt_i32_f32_e32 v28, v28
	v_cndmask_b32_e64 v29, 0, 1, s[38:39]
	v_med3_i32 v5, v5, s1, v118
	v_med3_i32 v8, v6, s1, v118
	v_med3_i32 v9, v7, s1, v118
	v_med3_i32 v6, v31, s1, v118
	v_med3_i32 v12, v38, s1, v118
	v_med3_i32 v13, v11, s1, v118
	v_med3_i32 v14, v39, s1, v118
	v_med3_i32 v7, v40, s1, v118
	v_med3_i32 v15, v41, s1, v118
	v_med3_i32 v16, v42, s1, v118
	v_med3_i32 v17, v43, s1, v118
	v_med3_i32 v11, v44, s1, v118
	v_med3_i32 v26, v26, s1, v118
	v_med3_i32 v27, v27, s1, v118
	v_cmp_ne_u32_e64 s[48:49], 1, v29
	s_andn2_b64 vcc, exec, s[38:39]
	v_med3_i32 v28, v28, s1, v118
	s_cbranch_vccnz .LBB0_51
	v_add_u32_e32 v29, v8, v5
	v_add3_u32 v29, v29, v9, v10
	v_add3_u32 v29, v29, v6, v12
	v_add3_u32 v29, v29, v13, v14
	v_add3_u32 v29, v29, v7, v15
	v_add3_u32 v29, v29, v16, v17
	v_add3_u32 v29, v29, v11, v26
	v_add3_u32 v29, v29, v27, v28
	ds_bpermute_b32 v30, v33, v29
	s_waitcnt lgkmcnt(0)
	v_add_u32_e32 v29, v30, v29
	ds_bpermute_b32 v30, v34, v29
	s_and_saveexec_b64 vcc, s[46:47]
	s_cbranch_execz .LBB0_50
	s_waitcnt lgkmcnt(0)
	v_add_u32_e32 v29, v29, v30
	v_lshl_add_u64 v[30:31], v[20:21], 2, s[44:45]
	global_atomic_add v[30:31], v29, off

; #define GAS __attribute__((address_space(1)))
; #define LAS __attribute__((address_space(3)))
; __device__ __forceinline__ int q8(float v) { int q = (int)rintf(v); q = q < -127 ? -127 : q; return q > 127 ? 127 : q; }
; __device__ __forceinline__ unsigned pkq4(int a, int b, int c, int d) { return (unsigned)(a & 255) | ((unsigned)(b & 255) << 8) | ((unsigned)(c & 255) << 16) | ((unsigned)d << 24); }
; __device__ __forceinline__ void transpose_item_q(const float* __restrict__ W, int K, int N, signed char* __restrict__ WQ, const float* __restrict__ gk, const unsigned* __restrict__ cmax, LAS float* scr, int item, int lane, int* csum = nullptr) {
;     ...
;     for (int j = 0; j < 2; ++j) { const int n = (lane >> 2) + 16 * j; const LAS float* s = scr + (16 * c) * 33 + n;
;         const float inv = 127.0f / fmaxf(__uint_as_float(cmax[n0 + n]), 1e-30f);
;         int q[16];
; #pragma unroll
;         for (int e = 0; e < 16; ++e) q[e] = q8(s[e * 33] * inv);
;         v4u o; o.x = pkq4(q[0], q[1], q[2], q[3]); o.y = pkq4(q[4], q[5], q[6], q[7]); o.z = pkq4(q[8], q[9], q[10], q[11]); o.w = pkq4(q[12], q[13], q[14], q[15]);
;         if (csum) { int t = 0;
; #pragma unroll
;             for (int e = 0; e < 16; ++e) t += q[e];
;             t += __builtin_amdgcn_ds_bpermute((lane ^ 1) << 2, t); t += __builtin_amdgcn_ds_bpermute((lane ^ 2) << 2, t);
;             if (c == 0) (void)__hip_atomic_fetch_add(csum + n0 + n, t, __ATOMIC_RELAXED, __HIP_MEMORY_SCOPE_AGENT); }
;         *(GAS v4u*)(WQ + ((((size_t)(n0 >> 8) * (K / 128) + (k0 >> 7)) * 256 + (n0 & 255) + n) * 128 + (k0 & 127) + 16 * c)) = o; }
.LBB0_51:
	v_mov_b32_e32 v38, v61
	s_mul_i32 s14, s84, s34
	s_add_i32 s14, s86, s14
	s_ashr_i32 s15, s34, 1
	v_lshlrev_b32_e32 v2, 8, v8
	v_lshlrev_b32_e32 v3, 16, v9
	s_ashr_i32 s14, s14, 3
	v_perm_b32 v5, v10, v5, s33
	s_waitcnt lgkmcnt(0)
	v_perm_b32 v30, v14, v6, s33
	v_lshlrev_b32_e32 v6, 8, v15
	s_ashr_i32 s19, s15, 31
	v_and_b32_e32 v2, 0xff00, v2
	v_and_b32_e32 v3, 0xff0000, v3
	s_mul_hi_i32 s34, s14, s73
	s_mul_i32 s14, s14, s73
	v_and_b32_e32 v42, 0xff00, v6
	v_or3_b32 v6, v5, v2, v3
	s_add_u32 s14, s14, s15
	v_lshlrev_b32_e32 v8, 8, v12
	v_lshlrev_b32_e32 v9, 16, v13
	v_lshlrev_b32_e32 v31, 16, v16
	s_addc_u32 s15, s34, s19
	v_perm_b32 v39, v17, v7, s33
	v_lshlrev_b32_e32 v7, 8, v26
	v_and_b32_e32 v8, 0xff00, v8
	v_and_b32_e32 v9, 0xff0000, v9
	v_and_b32_e32 v31, 0xff0000, v31
	s_and_b32 vcc_lo, s18, 0xe0
	s_lshl_b64 s[18:19], s[14:15], 8
	v_and_b32_e32 v43, 0xff00, v7
	v_or3_b32 v7, v30, v8, v9
	v_or3_b32 v8, v39, v42, v31
	s_or_b32 s18, s18, vcc_lo
	v_lshlrev_b32_e32 v40, 16, v27
	s_and_b32 s34, s31, 64
	v_lshl_add_u64 v[30:31], s[18:19], 0, v[20:21]
	v_perm_b32 v41, v28, v11, s33
	v_and_b32_e32 v40, 0xff0000, v40
	v_lshl_add_u64 v[2:3], v[22:23], 0, s[34:35]
	v_lshlrev_b64 v[30:31], 7, v[30:31]
	v_or3_b32 v9, v41, v43, v40
	v_lshl_add_u64 v[30:31], v[2:3], 0, v[30:31]
	ds_read2_b32 v[10:11], v35 offset0:16 offset1:49
	ds_read2_b32 v[12:13], v35 offset0:82 offset1:115
	ds_read2_b32 v[14:15], v35 offset0:148 offset1:181
	ds_read2_b32 v[16:17], v35 offset0:214 offset1:247
	ds_read2_b32 v[26:27], v4 offset0:24 offset1:57
	ds_read2_b32 v[28:29], v4 offset0:90 offset1:123
	global_store_dwordx4 v[30:31], v[6:9], off
	s_waitcnt vmcnt(1)
	v_max_f32_e32 v5, v38, v38
	v_max_f32_e32 v5, 0xda24260, v5
	v_div_scale_f32 v38, s[14:15], v5, v5, s0
	v_rcp_f32_e32 v39, v38
	v_div_scale_f32 v6, vcc, s0, v5, s0
	v_fma_f32 v7, -v38, v39, 1.0
	v_fmac_f32_e32 v39, v7, v39
	v_mul_f32_e32 v7, v6, v39
	v_fma_f32 v8, -v38, v7, v6
	v_fmac_f32_e32 v7, v8, v39
	v_fma_f32 v6, -v38, v7, v6
	v_div_fmas_f32 v6, v6, v39, v7
	v_div_fixup_f32 v30, v6, v5, s0
	s_waitcnt lgkmcnt(5)
	v_mul_f32_e32 v6, v30, v11
	s_waitcnt lgkmcnt(4)
	v_mul_f32_e32 v7, v30, v12
	s_waitcnt lgkmcnt(2)
	v_mul_f32_e32 v11, v30, v16
	v_mul_f32_e32 v12, v30, v17
	v_mul_f32_e32 v5, v10, v30
	v_mul_f32_e32 v8, v30, v13
	s_waitcnt lgkmcnt(1)
	v_mul_f32_e32 v13, v30, v26
	v_rndne_f32_e32 v7, v7
	v_rndne_f32_e32 v11, v11
	v_rndne_f32_e32 v12, v12
	v_rndne_f32_e32 v5, v5
	v_rndne_f32_e32 v13, v13
	v_cvt_i32_f32_e32 v7, v7
	v_cvt_i32_f32_e32 v16, v11
	v_cvt_i32_f32_e32 v17, v12
	v_cvt_i32_f32_e32 v5, v5
	v_cvt_i32_f32_e32 v26, v13
	v_mul_f32_e32 v10, v30, v15
	v_rndne_f32_e32 v10, v10
	v_cvt_i32_f32_e32 v15, v10
	v_med3_i32 v10, v7, s1, v118
	v_med3_i32 v7, v16, s1, v118
	v_med3_i32 v13, v17, s1, v118
	ds_read2_b32 v[16:17], v4 offset0:156 offset1:189
	v_mul_f32_e32 v9, v30, v14
	v_mul_f32_e32 v14, v30, v27
	v_med3_i32 v11, v5, s1, v118
	v_med3_i32 v5, v26, s1, v118
	s_waitcnt lgkmcnt(1)
	v_mul_f32_e32 v26, v30, v29
	v_rndne_f32_e32 v6, v6
	v_rndne_f32_e32 v8, v8
	v_rndne_f32_e32 v9, v9
	v_rndne_f32_e32 v14, v14
	v_rndne_f32_e32 v26, v26
	v_cvt_i32_f32_e32 v6, v6
	v_cvt_i32_f32_e32 v8, v8
	v_cvt_i32_f32_e32 v9, v9
	v_cvt_i32_f32_e32 v27, v14
	v_cvt_i32_f32_e32 v26, v26
	s_waitcnt lgkmcnt(0)
	v_mul_f32_e32 v16, v30, v16
	v_rndne_f32_e32 v16, v16
	v_med3_i32 v12, v6, s1, v118
	v_med3_i32 v14, v8, s1, v118
	v_med3_i32 v8, v9, s1, v118
	v_med3_i32 v9, v15, s1, v118
	v_med3_i32 v6, v27, s1, v118
	v_mul_f32_e32 v15, v30, v28
	v_cvt_i32_f32_e32 v28, v16
	v_med3_i32 v16, v26, s1, v118
	ds_read2_b32 v[26:27], v4 offset0:222 offset1:255
	v_mul_f32_e32 v17, v30, v17
	v_med3_i32 v4, v28, s1, v118
	v_rndne_f32_e32 v15, v15
	v_rndne_f32_e32 v17, v17
	s_waitcnt lgkmcnt(0)
	v_mul_f32_e32 v26, v30, v26
	v_rndne_f32_e32 v26, v26
	v_cvt_i32_f32_e32 v28, v26
	v_mul_f32_e32 v26, v30, v27
	v_rndne_f32_e32 v26, v26
	v_cvt_i32_f32_e32 v15, v15
	v_cvt_i32_f32_e32 v17, v17
	v_cvt_i32_f32_e32 v27, v26
	s_and_b64 vcc, exec, s[48:49]
	v_med3_i32 v15, v15, s1, v118
	v_med3_i32 v26, v17, s1, v118
	v_med3_i32 v17, v28, s1, v118
	v_med3_i32 v27, v27, s1, v118
	s_cbranch_vccnz .LBB0_30
	v_add_u32_e32 v28, v12, v11
	v_add3_u32 v28, v28, v10, v14
	v_add3_u32 v28, v28, v8, v9
	v_add3_u32 v28, v28, v7, v13
	v_add3_u32 v28, v28, v5, v6
	v_add3_u32 v28, v28, v15, v16
	v_add3_u32 v28, v28, v4, v26
	v_add3_u32 v28, v28, v17, v27
	ds_bpermute_b32 v29, v33, v28
	s_waitcnt lgkmcnt(0)
	v_add_u32_e32 v28, v29, v28
	ds_bpermute_b32 v29, v34, v28
	s_and_saveexec_b64 s[48:49], s[46:47]
	s_cbranch_execz .LBB0_29
	s_waitcnt lgkmcnt(0)
	v_add_u32_e32 v30, v28, v29
	v_lshl_add_u64 v[28:29], v[20:21], 2, s[44:45]
	global_atomic_add v[28:29], v30, off offset:64
	s_branch .LBB0_29
